# global attention loop: waves 4-7 barrier moved to mid-step (half-step skew vs waves 0-3 on the same SIMD)
# speedup vs baseline: 1.0059x; 1.0051x over previous
.Lgo_nv:
	s_add_i32 s72, s7, 2
	s_mul_hi_u32 s80, s72, 0x55555556
	s_mul_i32 s80, s80, 3
	s_sub_u32 s80, s72, s80
	s_lshl_b32 s81, s80, 13
	s_cmp_eq_u32 s80, 2
	s_cselect_b32 s81, 0x6000, s81
	v_add_u32_e32 v242, s81, v253
	s_add_i32 s72, s7, 1
	s_and_b32 s80, s72, 3
	s_lshl_b32 s81, s80, 13
	s_cmp_eq_u32 s80, 3
	s_cselect_b32 s81, 0xe000, s81
	v_add_u32_e32 v243, s81, v221
	ds_read_b64_tr_b16 v[160:161], v242 offset:24576
	ds_read_b64_tr_b16 v[162:163], v242 offset:25088
	ds_read_b64_tr_b16 v[164:165], v242 offset:25600
	ds_read_b64_tr_b16 v[166:167], v242 offset:26112
	ds_read_b64_tr_b16 v[168:169], v242 offset:26624
	ds_read_b64_tr_b16 v[170:171], v242 offset:27136
	ds_read_b64_tr_b16 v[172:173], v242 offset:27648
	ds_read_b64_tr_b16 v[174:175], v242 offset:28160
	v_mfma_f32_32x32x16_bf16 v[80:95], v[128:131], v[96:99], 0
	v_add_f32_e32 v204, v204, v32
	v_add_f32_e32 v205, v205, v33
	v_add_f32_e32 v208, v208, v34
	v_add_f32_e32 v209, v209, v35
	v_cvt_pk_bf16_f32 v112, v32, v33
	v_cvt_pk_bf16_f32 v113, v34, v35
	v_mfma_f32_32x32x16_bf16 v[48:63], v[132:135], v[96:99], 0
	v_add_f32_e32 v204, v204, v36
	v_add_f32_e32 v205, v205, v37
	v_add_f32_e32 v208, v208, v38
	v_add_f32_e32 v209, v209, v39
	v_cvt_pk_bf16_f32 v114, v36, v37
	v_cvt_pk_bf16_f32 v115, v38, v39
	v_mfma_f32_32x32x16_bf16 v[80:95], v[136:139], v[100:103], v[80:95]
	v_add_f32_e32 v204, v204, v40
	v_add_f32_e32 v205, v205, v41
	v_add_f32_e32 v208, v208, v42
	v_add_f32_e32 v209, v209, v43
	v_cvt_pk_bf16_f32 v116, v40, v41
	v_cvt_pk_bf16_f32 v117, v42, v43
	v_mfma_f32_32x32x16_bf16 v[48:63], v[140:143], v[100:103], v[48:63]
	ds_read_b64_tr_b16 v[176:177], v242 offset:28672
	ds_read_b64_tr_b16 v[178:179], v242 offset:29184
	ds_read_b64_tr_b16 v[180:181], v242 offset:29696
	ds_read_b64_tr_b16 v[182:183], v242 offset:30208
	ds_read_b64_tr_b16 v[184:185], v242 offset:30720
	ds_read_b64_tr_b16 v[186:187], v242 offset:31232
	ds_read_b64_tr_b16 v[188:189], v242 offset:31744
	s_waitcnt lgkmcnt(14)
	ds_read_b64_tr_b16 v[190:191], v242 offset:32256
	v_add_f32_e32 v204, v204, v44
	v_add_f32_e32 v205, v205, v45
	v_add_f32_e32 v208, v208, v46
	v_add_f32_e32 v209, v209, v47
	v_cvt_pk_bf16_f32 v118, v44, v45
	v_cvt_pk_bf16_f32 v119, v46, v47
	v_mfma_f32_32x32x16_bf16 v[80:95], v[144:147], v[104:107], v[80:95]
	v_add_f32_e32 v204, v204, v64
	v_add_f32_e32 v205, v205, v65
	v_add_f32_e32 v208, v208, v66
	v_add_f32_e32 v209, v209, v67
	v_cvt_pk_bf16_f32 v120, v64, v65
	v_cvt_pk_bf16_f32 v121, v66, v67
	v_mfma_f32_32x32x16_bf16 v[48:63], v[148:151], v[104:107], v[48:63]
	v_add_f32_e32 v204, v204, v68
	v_add_f32_e32 v205, v205, v69
	v_add_f32_e32 v208, v208, v70
	v_add_f32_e32 v209, v209, v71
	v_cvt_pk_bf16_f32 v122, v68, v69
	v_cvt_pk_bf16_f32 v123, v70, v71
	v_mfma_f32_32x32x16_bf16 v[80:95], v[152:155], v[108:111], v[80:95]
	v_add_f32_e32 v204, v204, v72
	v_add_f32_e32 v205, v205, v73
	v_add_f32_e32 v208, v208, v74
	v_add_f32_e32 v209, v209, v75
	v_cvt_pk_bf16_f32 v124, v72, v73
	v_cvt_pk_bf16_f32 v125, v74, v75
	v_mfma_f32_32x32x16_bf16 v[48:63], v[156:159], v[108:111], v[48:63]
	v_add_f32_e32 v204, v204, v76
	v_add_f32_e32 v205, v205, v77
	v_add_f32_e32 v208, v208, v78
	v_add_f32_e32 v209, v209, v79
	v_cvt_pk_bf16_f32 v126, v76, v77
	v_cvt_pk_bf16_f32 v127, v78, v79
	s_cmp_lt_u32 s100, 0x1000
	s_cbranch_scc1 .Lgo_ms
	s_waitcnt lgkmcnt(0)
	s_and_b64 vcc, exec, s[82:83]
	s_cbranch_vccz .Lgo_m0
	s_waitcnt vmcnt(2)
	s_branch .Lgo_m1

.Lgo_ms:
	s_waitcnt lgkmcnt(14)
	v_mfma_f32_32x32x16_bf16 v[0:15], v[160:163], v[112:115], v[0:15]
	v_exp_f32_e32 v80, v80
	v_exp_f32_e32 v81, v81
	v_exp_f32_e32 v82, v82
	v_exp_f32_e32 v83, v83
	s_waitcnt lgkmcnt(12)
	v_mfma_f32_32x32x16_bf16 v[0:15], v[164:167], v[116:119], v[0:15]
	v_exp_f32_e32 v84, v84
	v_exp_f32_e32 v85, v85
	v_exp_f32_e32 v86, v86
	v_exp_f32_e32 v87, v87
	s_waitcnt lgkmcnt(10)
	v_mfma_f32_32x32x16_bf16 v[0:15], v[168:171], v[120:123], v[0:15]
	v_exp_f32_e32 v88, v88
	v_exp_f32_e32 v89, v89
	v_exp_f32_e32 v90, v90
	v_exp_f32_e32 v91, v91
	ds_read_b128 v[128:131], v243
	ds_read_b128 v[132:135], v243 offset:512
	s_waitcnt lgkmcnt(10)
	v_mfma_f32_32x32x16_bf16 v[0:15], v[172:175], v[124:127], v[0:15]
	v_exp_f32_e32 v92, v92
	v_exp_f32_e32 v93, v93
	v_exp_f32_e32 v94, v94
	v_exp_f32_e32 v95, v95
	ds_read_b128 v[136:139], v243 offset:2048
	ds_read_b128 v[140:143], v243 offset:2560
	s_waitcnt lgkmcnt(10)
	v_mfma_f32_32x32x16_bf16 v[16:31], v[176:179], v[112:115], v[16:31]
	v_exp_f32_e32 v48, v48
	v_exp_f32_e32 v49, v49
	v_exp_f32_e32 v50, v50
	v_exp_f32_e32 v51, v51
	ds_read_b128 v[144:147], v243 offset:4096
	ds_read_b128 v[148:151], v243 offset:4608
	s_waitcnt lgkmcnt(10)
	v_mfma_f32_32x32x16_bf16 v[16:31], v[180:183], v[116:119], v[16:31]
	v_exp_f32_e32 v52, v52
	v_exp_f32_e32 v53, v53
	v_exp_f32_e32 v54, v54
	v_exp_f32_e32 v55, v55
	ds_read_b128 v[152:155], v243 offset:6144
	ds_read_b128 v[156:159], v243 offset:6656
	s_waitcnt lgkmcnt(10)
	v_mfma_f32_32x32x16_bf16 v[16:31], v[184:187], v[120:123], v[16:31]
	v_exp_f32_e32 v56, v56
	v_exp_f32_e32 v57, v57
	v_exp_f32_e32 v58, v58
	v_exp_f32_e32 v59, v59
	s_waitcnt lgkmcnt(8)
	v_mfma_f32_32x32x16_bf16 v[16:31], v[188:191], v[124:127], v[16:31]
	v_exp_f32_e32 v60, v60
	v_exp_f32_e32 v61, v61
	v_exp_f32_e32 v62, v62
	v_exp_f32_e32 v63, v63
	s_waitcnt lgkmcnt(0)
	s_cmp_lt_u32 s100, 0x1000
	s_cbranch_scc0 .Lgo_nb
	s_and_b64 vcc, exec, s[82:83]
	s_cbranch_vccz .Lgo_w0
	s_waitcnt vmcnt(2)
	s_branch .Lgo_w1

; template <bool NOMAX> ...
;     ...
;         for (int t = 1; t < NF; t += 2) {
;             ATT_STEP(t, kreg, vreg, kregB, vregB, e0, e1, c0, c1);
;             if (t + 1 < NF) ATT_STEP(t + 1, kregB, vregB, kreg, vreg, c0, c1, e0, e1);
.Lgo_nb:
	s_add_i32 s7, s7, 1
	s_cmp_ge_i32 s7, s71
	s_cbranch_scc1 .Lg_drainB
	s_add_i32 s96, s7, 3
	s_cmp_lt_i32 s96, s71
	s_cselect_b64 s[82:83], -1, 0
	s_cbranch_scc0 .Lge_nk
	s_cmp_lg_u32 s96, 4
	s_cbranch_scc1 .Lge_ks
	v_mad_i64_i32 v[244:245], s[80:81], s84, v215, v[198:199]
	v_ashrrev_i32_e32 v243, 31, v248
	v_mov_b32_e32 v242, v248
	v_lshl_add_u64 v[244:245], v[242:243], 0, v[244:245]

.Lge_nv:
	s_add_i32 s72, s7, 2
	s_mul_hi_u32 s80, s72, 0x55555556
	s_mul_i32 s80, s80, 3
	s_sub_u32 s80, s72, s80
	s_lshl_b32 s81, s80, 13
	s_cmp_eq_u32 s80, 2
	s_cselect_b32 s81, 0x6000, s81
	v_add_u32_e32 v242, s81, v253
	s_add_i32 s72, s7, 1
	s_and_b32 s80, s72, 3
	s_lshl_b32 s81, s80, 13
	s_cmp_eq_u32 s80, 3
	s_cselect_b32 s81, 0xe000, s81
	v_add_u32_e32 v243, s81, v221
	ds_read_b64_tr_b16 v[160:161], v242 offset:24576
	ds_read_b64_tr_b16 v[162:163], v242 offset:25088
	ds_read_b64_tr_b16 v[164:165], v242 offset:25600
	ds_read_b64_tr_b16 v[166:167], v242 offset:26112
	ds_read_b64_tr_b16 v[168:169], v242 offset:26624
	ds_read_b64_tr_b16 v[170:171], v242 offset:27136
	ds_read_b64_tr_b16 v[172:173], v242 offset:27648
	ds_read_b64_tr_b16 v[174:175], v242 offset:28160
	v_mfma_f32_32x32x16_bf16 v[32:47], v[128:131], v[96:99], 0
	v_add_f32_e32 v204, v204, v80
	v_add_f32_e32 v205, v205, v81
	v_add_f32_e32 v208, v208, v82
	v_add_f32_e32 v209, v209, v83
	v_cvt_pk_bf16_f32 v112, v80, v81
	v_cvt_pk_bf16_f32 v113, v82, v83
	v_mfma_f32_32x32x16_bf16 v[64:79], v[132:135], v[96:99], 0
	v_add_f32_e32 v204, v204, v84
	v_add_f32_e32 v205, v205, v85
	v_add_f32_e32 v208, v208, v86
	v_add_f32_e32 v209, v209, v87
	v_cvt_pk_bf16_f32 v114, v84, v85
	v_cvt_pk_bf16_f32 v115, v86, v87
	v_mfma_f32_32x32x16_bf16 v[32:47], v[136:139], v[100:103], v[32:47]
	v_add_f32_e32 v204, v204, v88
	v_add_f32_e32 v205, v205, v89
	v_add_f32_e32 v208, v208, v90
	v_add_f32_e32 v209, v209, v91
	v_cvt_pk_bf16_f32 v116, v88, v89
	v_cvt_pk_bf16_f32 v117, v90, v91
	v_mfma_f32_32x32x16_bf16 v[64:79], v[140:143], v[100:103], v[64:79]
	ds_read_b64_tr_b16 v[176:177], v242 offset:28672
	ds_read_b64_tr_b16 v[178:179], v242 offset:29184
	ds_read_b64_tr_b16 v[180:181], v242 offset:29696
	ds_read_b64_tr_b16 v[182:183], v242 offset:30208
	ds_read_b64_tr_b16 v[184:185], v242 offset:30720
	ds_read_b64_tr_b16 v[186:187], v242 offset:31232
	ds_read_b64_tr_b16 v[188:189], v242 offset:31744
	s_waitcnt lgkmcnt(14)
	ds_read_b64_tr_b16 v[190:191], v242 offset:32256
	v_add_f32_e32 v204, v204, v92
	v_add_f32_e32 v205, v205, v93
	v_add_f32_e32 v208, v208, v94
	v_add_f32_e32 v209, v209, v95
	v_cvt_pk_bf16_f32 v118, v92, v93
	v_cvt_pk_bf16_f32 v119, v94, v95
	v_mfma_f32_32x32x16_bf16 v[32:47], v[144:147], v[104:107], v[32:47]
	v_add_f32_e32 v204, v204, v48
	v_add_f32_e32 v205, v205, v49
	v_add_f32_e32 v208, v208, v50
	v_add_f32_e32 v209, v209, v51
	v_cvt_pk_bf16_f32 v120, v48, v49
	v_cvt_pk_bf16_f32 v121, v50, v51
	v_mfma_f32_32x32x16_bf16 v[64:79], v[148:151], v[104:107], v[64:79]
	v_add_f32_e32 v204, v204, v52
	v_add_f32_e32 v205, v205, v53
	v_add_f32_e32 v208, v208, v54
	v_add_f32_e32 v209, v209, v55
	v_cvt_pk_bf16_f32 v122, v52, v53
	v_cvt_pk_bf16_f32 v123, v54, v55
	v_mfma_f32_32x32x16_bf16 v[32:47], v[152:155], v[108:111], v[32:47]
	v_add_f32_e32 v204, v204, v56
	v_add_f32_e32 v205, v205, v57
	v_add_f32_e32 v208, v208, v58
	v_add_f32_e32 v209, v209, v59
	v_cvt_pk_bf16_f32 v124, v56, v57
	v_cvt_pk_bf16_f32 v125, v58, v59
	v_mfma_f32_32x32x16_bf16 v[64:79], v[156:159], v[108:111], v[64:79]
	v_add_f32_e32 v204, v204, v60
	v_add_f32_e32 v205, v205, v61
	v_add_f32_e32 v208, v208, v62
	v_add_f32_e32 v209, v209, v63
	v_cvt_pk_bf16_f32 v126, v60, v61
	v_cvt_pk_bf16_f32 v127, v62, v63
	s_cmp_lt_u32 s100, 0x1000
	s_cbranch_scc1 .Lge_ms
	s_waitcnt lgkmcnt(0)
	s_and_b64 vcc, exec, s[82:83]
	s_cbranch_vccz .Lge_m0
	s_waitcnt vmcnt(2)
	s_branch .Lge_m1

.Lge_ms:
	s_waitcnt lgkmcnt(14)
	v_mfma_f32_32x32x16_bf16 v[0:15], v[160:163], v[112:115], v[0:15]
	v_exp_f32_e32 v32, v32
	v_exp_f32_e32 v33, v33
	v_exp_f32_e32 v34, v34
	v_exp_f32_e32 v35, v35
	s_waitcnt lgkmcnt(12)
	v_mfma_f32_32x32x16_bf16 v[0:15], v[164:167], v[116:119], v[0:15]
	v_exp_f32_e32 v36, v36
	v_exp_f32_e32 v37, v37
	v_exp_f32_e32 v38, v38
	v_exp_f32_e32 v39, v39
	s_waitcnt lgkmcnt(10)
	v_mfma_f32_32x32x16_bf16 v[0:15], v[168:171], v[120:123], v[0:15]
	v_exp_f32_e32 v40, v40
	v_exp_f32_e32 v41, v41
	v_exp_f32_e32 v42, v42
	v_exp_f32_e32 v43, v43
	ds_read_b128 v[128:131], v243
	ds_read_b128 v[132:135], v243 offset:512
	s_waitcnt lgkmcnt(10)
	v_mfma_f32_32x32x16_bf16 v[0:15], v[172:175], v[124:127], v[0:15]
	v_exp_f32_e32 v44, v44
	v_exp_f32_e32 v45, v45
	v_exp_f32_e32 v46, v46
	v_exp_f32_e32 v47, v47
	ds_read_b128 v[136:139], v243 offset:2048
	ds_read_b128 v[140:143], v243 offset:2560
	s_waitcnt lgkmcnt(10)
	v_mfma_f32_32x32x16_bf16 v[16:31], v[176:179], v[112:115], v[16:31]
	v_exp_f32_e32 v64, v64
	v_exp_f32_e32 v65, v65
	v_exp_f32_e32 v66, v66
	v_exp_f32_e32 v67, v67
	ds_read_b128 v[144:147], v243 offset:4096
	ds_read_b128 v[148:151], v243 offset:4608
	s_waitcnt lgkmcnt(10)
	v_mfma_f32_32x32x16_bf16 v[16:31], v[180:183], v[116:119], v[16:31]
	v_exp_f32_e32 v68, v68
	v_exp_f32_e32 v69, v69
	v_exp_f32_e32 v70, v70
	v_exp_f32_e32 v71, v71
	ds_read_b128 v[152:155], v243 offset:6144
	ds_read_b128 v[156:159], v243 offset:6656
	s_waitcnt lgkmcnt(10)
	v_mfma_f32_32x32x16_bf16 v[16:31], v[184:187], v[120:123], v[16:31]
	v_exp_f32_e32 v72, v72
	v_exp_f32_e32 v73, v73
	v_exp_f32_e32 v74, v74
	v_exp_f32_e32 v75, v75
	s_waitcnt lgkmcnt(8)
	v_mfma_f32_32x32x16_bf16 v[16:31], v[188:191], v[124:127], v[16:31]
	v_exp_f32_e32 v76, v76
	v_exp_f32_e32 v77, v77
	v_exp_f32_e32 v78, v78
	v_exp_f32_e32 v79, v79
	s_waitcnt lgkmcnt(0)
	s_cmp_lt_u32 s100, 0x1000
	s_cbranch_scc0 .Lge_nb
	s_and_b64 vcc, exec, s[82:83]
	s_cbranch_vccz .Lge_w0
	s_waitcnt vmcnt(2)
	s_branch .Lge_w1

; #define ATT_LAS __attribute__((address_space(3)))
; __device__ __forceinline__ unsigned pk_bf16(float lo, float hi) { unsigned r; asm volatile("v_cvt_pk_bf16_f32 %0, %1, %2" : "=v"(r) : "v"(lo), "v"(hi)); return r; }
; template <bool NOMAX> ...
;     ...
;         for (int t = 1; t < NF; t += 2) {
;             ATT_STEP(t, kreg, vreg, kregB, vregB, e0, e1, c0, c1);
;             if (t + 1 < NF) ATT_STEP(t + 1, kregB, vregB, kreg, vreg, c0, c1, e0, e1);
;         }
;         if ((NF - 1) & 1) { e0 = c0; e1 = c1; }
;     ...
;         { u32x4 pw[4]; float sacc = 0.f;
; #pragma unroll
;           for (int r = 0; r < 16; ++r) sacc += e0[r] + e1[r];
;           lsum += sacc;
; #pragma unroll
;           for (int j = 0; j < 4; ++j) { pw[0][j] = pk_bf16(e0[2 * j], e0[2 * j + 1]); pw[1][j] = pk_bf16(e0[8 + 2 * j], e0[8 + 2 * j + 1]);
;                                         pw[2][j] = pk_bf16(e1[2 * j], e1[2 * j + 1]); pw[3][j] = pk_bf16(e1[8 + 2 * j], e1[8 + 2 * j + 1]); }
;           const ATT_LAS unsigned char* vb = ATT_VBUF((NF - 1) & 1) + vlane;
; #pragma unroll
;           for (int s = 0; s < 4; ++s) { const bf16x8 pa = __builtin_bit_cast(bf16x8, pw[s]);
;               { const s16x4 lo = vtr(vb + s * 1024), h4 = vtr(vb + s * 1024 + 512); const bf16x8 vf = (bf16x8){lo[0], lo[1], lo[2], lo[3], h4[0], h4[1], h4[2], h4[3]};
;                 o0 = __builtin_amdgcn_mfma_f32_32x32x16_bf16(vf, pa, o0, 0, 0, 0); }
;               { const s16x4 lo = vtr(vb + 4096 + s * 1024), h4 = vtr(vb + 4096 + s * 1024 + 512); const bf16x8 vf = (bf16x8){lo[0], lo[1], lo[2], lo[3], h4[0], h4[1], h4[2], h4[3]};
;                 o1 = __builtin_amdgcn_mfma_f32_32x32x16_bf16(vf, pa, o1, 0, 0, 0); } }
.Lge_nb:
	s_add_i32 s7, s7, 1
	s_cmp_lt_i32 s7, s71
	s_cbranch_scc1 .Lg_loop
	s_add_i32 s72, s7, 2
	s_mul_hi_u32 s80, s72, 0x55555556
	s_mul_i32 s80, s80, 3
	s_sub_u32 s80, s72, s80
	s_lshl_b32 s81, s80, 13
	s_cmp_eq_u32 s80, 2
	s_cselect_b32 s81, 0x6000, s81
	v_add_u32_e32 v242, s81, v253
	ds_read_b64_tr_b16 v[160:161], v242 offset:24576
	ds_read_b64_tr_b16 v[162:163], v242 offset:25088
	ds_read_b64_tr_b16 v[164:165], v242 offset:25600
	ds_read_b64_tr_b16 v[166:167], v242 offset:26112
	ds_read_b64_tr_b16 v[168:169], v242 offset:26624
	ds_read_b64_tr_b16 v[170:171], v242 offset:27136
	ds_read_b64_tr_b16 v[172:173], v242 offset:27648
	ds_read_b64_tr_b16 v[174:175], v242 offset:28160
	v_add_f32_e32 v204, v204, v32
	v_add_f32_e32 v205, v205, v33
	v_add_f32_e32 v208, v208, v34
	v_add_f32_e32 v209, v209, v35
	v_add_f32_e32 v204, v204, v36
	v_add_f32_e32 v205, v205, v37
	v_add_f32_e32 v208, v208, v38
	v_add_f32_e32 v209, v209, v39
	v_add_f32_e32 v204, v204, v40
	v_add_f32_e32 v205, v205, v41
	v_add_f32_e32 v208, v208, v42
	v_add_f32_e32 v209, v209, v43
	v_add_f32_e32 v204, v204, v44
	v_add_f32_e32 v205, v205, v45
	v_add_f32_e32 v208, v208, v46
	v_add_f32_e32 v209, v209, v47
	v_add_f32_e32 v204, v204, v64
	v_add_f32_e32 v205, v205, v65
	v_add_f32_e32 v208, v208, v66
	v_add_f32_e32 v209, v209, v67
	v_add_f32_e32 v204, v204, v68
	v_add_f32_e32 v205, v205, v69
	v_add_f32_e32 v208, v208, v70
	v_add_f32_e32 v209, v209, v71
	v_add_f32_e32 v204, v204, v72
	v_add_f32_e32 v205, v205, v73
	v_add_f32_e32 v208, v208, v74
	v_add_f32_e32 v209, v209, v75
	v_add_f32_e32 v204, v204, v76
	v_add_f32_e32 v205, v205, v77
	v_add_f32_e32 v208, v208, v78
	v_add_f32_e32 v209, v209, v79
	v_cvt_pk_bf16_f32 v112, v32, v33
	v_cvt_pk_bf16_f32 v113, v34, v35
	v_cvt_pk_bf16_f32 v114, v36, v37
	v_cvt_pk_bf16_f32 v115, v38, v39
	v_cvt_pk_bf16_f32 v116, v40, v41
	v_cvt_pk_bf16_f32 v117, v42, v43
	v_cvt_pk_bf16_f32 v118, v44, v45
	v_cvt_pk_bf16_f32 v119, v46, v47
	v_cvt_pk_bf16_f32 v120, v64, v65
	v_cvt_pk_bf16_f32 v121, v66, v67
	v_cvt_pk_bf16_f32 v122, v68, v69
	v_cvt_pk_bf16_f32 v123, v70, v71
	v_cvt_pk_bf16_f32 v124, v72, v73
	v_cvt_pk_bf16_f32 v125, v74, v75
	v_cvt_pk_bf16_f32 v126, v76, v77
	v_cvt_pk_bf16_f32 v127, v78, v79
	ds_read_b64_tr_b16 v[176:177], v242 offset:28672
	ds_read_b64_tr_b16 v[178:179], v242 offset:29184
	ds_read_b64_tr_b16 v[180:181], v242 offset:29696
	ds_read_b64_tr_b16 v[182:183], v242 offset:30208
	ds_read_b64_tr_b16 v[184:185], v242 offset:30720
	ds_read_b64_tr_b16 v[186:187], v242 offset:31232
	ds_read_b64_tr_b16 v[188:189], v242 offset:31744
	s_waitcnt lgkmcnt(14)
	ds_read_b64_tr_b16 v[190:191], v242 offset:32256
	s_waitcnt lgkmcnt(0)
	v_mfma_f32_32x32x16_bf16 v[0:15], v[160:163], v[112:115], v[0:15]
	v_mfma_f32_32x32x16_bf16 v[0:15], v[164:167], v[116:119], v[0:15]
	v_mfma_f32_32x32x16_bf16 v[0:15], v[168:171], v[120:123], v[0:15]
	v_mfma_f32_32x32x16_bf16 v[0:15], v[172:175], v[124:127], v[0:15]
	v_mfma_f32_32x32x16_bf16 v[16:31], v[176:179], v[112:115], v[16:31]
	v_mfma_f32_32x32x16_bf16 v[16:31], v[180:183], v[116:119], v[16:31]
	v_mfma_f32_32x32x16_bf16 v[16:31], v[184:187], v[120:123], v[16:31]
	v_mfma_f32_32x32x16_bf16 v[16:31], v[188:191], v[124:127], v[16:31]
	s_branch .Lg_done
